# XCD-aware tile order for N=1024 GEMMs (down, out-proj): the 8 workgroups sharing an A row panel run on one XCD
# speedup vs baseline: 1.1854x; 1.0254x over previous
; template <class Epi>
; __device__ __forceinline__ void gemm_tile(const bf16_t* __restrict__ A, const bf16_t* __restrict__ Bt, int K, int row0, int col0, const Epi& epi, char* smem,
;                                           bool prefetched, bool nvalid, int nrow0, int ncol0) {
;     ...
;     const bf16_t* pA = A + (size_t)row0 * K;
;     const bf16_t* pB = Bt + (size_t)col0 * K;
;     ...
;     int offA[4][2], offB[4][2];
; #pragma unroll
;     for (int m = 0; m < 4; ++m)
; #pragma unroll
;         for (int ks = 0; ks < 2; ++ks) { const int cx = ((ks * 4 + fq) ^ ((fr >> 1) & 7)) * 16;
;             offA[m][ks] = (wr * 64 + m * 16 + fr) * 128 + cx;
;             offB[m][ks] = TILE_B + (wc * 64 + (m >> 1) * 32 + 8 * (fr >> 2) + 4 * (m & 1) + (fr & 3)) * 128 + cx; }
;     if (prefetched) {
;         if (Epi::STAGED) asm volatile("s_waitcnt vmcnt(8)" ::: "memory");
;         else asm volatile("s_waitcnt vmcnt(0)" ::: "memory");
;     } else {
;         GLDS_STAGE(0, pA, pB, 0);
;         asm volatile("s_waitcnt vmcnt(0)" ::: "memory");
; template <class Epi>
; __device__ __forceinline__ void gemm_phase(const bf16_t* A, const bf16_t* Bt, int M, int N, int K, const Epi& epi, char* smem) {
;     ...
;     for (int i = blockIdx.x; i < ntiles; i += G) {
;         const int j = i + G; const bool nv = j < ntiles;
;         gemm_tile(A, Bt, K, (i / nN) << 7, (i % nN) << 7, epi, smem, pre, nv, (j / nN) << 7, (j % nN) << 7);
.LBB0_455:
	s_and_b32 s4, s16, 7
	s_lshl_b32 s4, s4, 3
	s_bfe_u32 s5, s16, 0x30003
	s_or_b32 s4, s4, s5
	s_and_b32 s5, s16, 0xffffffc0
	s_or_b32 s5, s4, s5
	s_ashr_i32 s0, s5, 31
	s_lshr_b32 s0, s0, 29
	s_add_i32 s1, s5, s0
	s_lshl_b32 s0, s1, 4
	s_and_b32 s1, s1, 0x1fffff8
	s_sub_i32 s1, s5, s1
	s_and_b32 s0, s0, 0xffffff80
	s_lshl_b32 s4, s1, 7
	s_ashr_i32 s1, s0, 31
	s_ashr_i32 s5, s4, 31
	s_lshl_b64 s[8:9], s[0:1], 11
	s_lshl_b64 s[6:7], s[4:5], 11
	s_mov_b64 s[12:13], -1
	s_and_b64 vcc, exec, s[10:11]
	s_cbranch_vccnz .LBB0_457
	v_readlane_b32 s10, v245, 60
	v_readlane_b32 s11, v245, 61
	s_add_u32 s10, s10, s8
	s_addc_u32 s11, s11, s9
	s_add_u32 s12, s14, s6
	v_readfirstlane_b32 s1, v149
	s_addc_u32 s13, s15, s7
	s_mov_b32 m0, s1
	v_readfirstlane_b32 s1, v119
	global_load_lds_dwordx4 v126, s[10:11]
	v_lshl_add_u64 v[0:1], v[64:65], 1, s[12:13]
	s_mov_b32 m0, s1
	v_readfirstlane_b32 s1, v120
	global_load_lds_dwordx4 v[0:1], off
	s_mov_b32 m0, s1
	v_readfirstlane_b32 s1, v121
	global_load_lds_dwordx4 v127, s[10:11]
	v_lshl_add_u64 v[0:1], v[66:67], 1, s[12:13]
	s_mov_b32 m0, s1
	v_readfirstlane_b32 s1, v122
	global_load_lds_dwordx4 v[0:1], off
	s_mov_b32 m0, s1
	v_readfirstlane_b32 s1, v123
	global_load_lds_dwordx4 v128, s[10:11]
	v_lshl_add_u64 v[0:1], v[68:69], 1, s[12:13]
	s_mov_b32 m0, s1
	v_readfirstlane_b32 s1, v124
	global_load_lds_dwordx4 v[0:1], off
	s_mov_b32 m0, s1
	v_readfirstlane_b32 s1, v125
	global_load_lds_dwordx4 v129, s[10:11]
	v_lshl_add_u64 v[0:1], v[70:71], 1, s[12:13]
	s_mov_b32 m0, s1
	s_mov_b64 s[12:13], 0
	global_load_lds_dwordx4 v[0:1], off
	s_waitcnt vmcnt(0)

; __device__ __forceinline__ f32x4 mfma16(bf16x8 a, bf16x8 b, f32x4 c) { return __builtin_amdgcn_mfma_f32_16x16x32_bf16(a, b, c, 0, 0, 0); }
; template <class Epi>
; __device__ __forceinline__ void gemm_tile(const bf16_t* __restrict__ A, const bf16_t* __restrict__ Bt, int K, int row0, int col0, const Epi& epi, char* smem,
;                                           bool prefetched, bool nvalid, int nrow0, int ncol0) {
;     ...
;         for (int ks = 0; ks < 2; ++ks) {
;             bf16x8 a[4], b[4];
; #pragma unroll
;             for (int m = 0; m < 4; ++m) a[m] = *(const bf16x8*)(cb + offA[m][ks]);
; #pragma unroll
;             for (int n = 0; n < 4; ++n) b[n] = *(const bf16x8*)(cb + offB[n][ks]);
; #pragma unroll
;             for (int m = 0; m < 4; ++m)
; #pragma unroll
;                 for (int n = 0; n < 4; ++n) acc[m][n] = mfma16(b[n], a[m], acc[m][n]);
;         }
;         asm volatile("s_waitcnt vmcnt(0)" ::: "memory");
;         __syncthreads();
;     }
;     if (nvalid) { const bf16_t* qA = A + (size_t)nrow0 * K; const bf16_t* qB = Bt + (size_t)ncol0 * K; GLDS_STAGE(0, qA, qB, 0); }
; template <class Epi>
; __device__ __forceinline__ void gemm_phase(const bf16_t* A, const bf16_t* Bt, int M, int N, int K, const Epi& epi, char* smem) {
;     ...
;     for (int i = blockIdx.x; i < ntiles; i += G) {
;         const int j = i + G; const bool nv = j < ntiles;
;         gemm_tile(A, Bt, K, (i / nN) << 7, (i % nN) << 7, epi, smem, pre, nv, (j / nN) << 7, (j % nN) << 7);
;         pre = nv;
.Lgk_tail_460:
	v_mfma_f32_16x16x32_bf16 v[32:35], v[142:145], v[246:249], v[32:35]
	v_mfma_f32_16x16x32_bf16 v[36:39], v[162:165], v[246:249], v[36:39]
	v_mfma_f32_16x16x32_bf16 v[40:43], v[166:169], v[246:249], v[40:43]
	v_mfma_f32_16x16x32_bf16 v[44:47], v[170:173], v[246:249], v[44:47]
	v_mfma_f32_16x16x32_bf16 v[48:51], v[142:145], v[250:253], v[48:51]
	v_mfma_f32_16x16x32_bf16 v[52:55], v[162:165], v[250:253], v[52:55]
	v_mfma_f32_16x16x32_bf16 v[56:59], v[166:169], v[250:253], v[56:59]
	v_mfma_f32_16x16x32_bf16 v[60:63], v[170:173], v[250:253], v[60:63]
	ds_read_b128 v[94:97], v87 offset:49152
	ds_read_b128 v[98:101], v87 offset:49664
	ds_read_b128 v[102:105], v110 offset:32768
	ds_read_b128 v[106:109], v110 offset:34816
	ds_read_b128 v[142:145], v87 offset:53248
	ds_read_b128 v[162:165], v87 offset:53760
	s_add_i32 s16, s16, s58
	s_waitcnt lgkmcnt(3)
	v_mfma_f32_16x16x32_bf16 v[0:3], v[94:97], v[102:105], v[0:3]
	s_cmpk_gt_i32 s16, 0x7ff
	s_cselect_b64 s[6:7], -1, 0
	s_cmpk_lt_i32 s16, 0x800
	v_mfma_f32_16x16x32_bf16 v[4:7], v[98:101], v[102:105], v[4:7]
	s_waitcnt lgkmcnt(1)
	v_mfma_f32_16x16x32_bf16 v[8:11], v[142:145], v[102:105], v[8:11]
	s_waitcnt lgkmcnt(0)
	v_mfma_f32_16x16x32_bf16 v[12:15], v[162:165], v[102:105], v[12:15]
	v_mfma_f32_16x16x32_bf16 v[16:19], v[94:97], v[106:109], v[16:19]
	v_mfma_f32_16x16x32_bf16 v[20:23], v[98:101], v[106:109], v[20:23]
	v_mfma_f32_16x16x32_bf16 v[24:27], v[142:145], v[106:109], v[24:27]
	v_mfma_f32_16x16x32_bf16 v[28:31], v[162:165], v[106:109], v[28:31]
	ds_read_b128 v[102:105], v110 offset:36864
	ds_read_b128 v[106:109], v110 offset:38912
	ds_read_b128 v[178:181], v118 offset:49152
	s_waitcnt lgkmcnt(2)
	v_mfma_f32_16x16x32_bf16 v[166:169], v[94:97], v[102:105], v[32:35]
	v_mfma_f32_16x16x32_bf16 v[170:173], v[98:101], v[102:105], v[36:39]
	v_mfma_f32_16x16x32_bf16 v[174:177], v[142:145], v[102:105], v[40:43]
	v_mfma_f32_16x16x32_bf16 v[102:105], v[162:165], v[102:105], v[44:47]
	s_waitcnt lgkmcnt(1)
	v_mfma_f32_16x16x32_bf16 v[94:97], v[94:97], v[106:109], v[48:51]
	v_mfma_f32_16x16x32_bf16 v[98:101], v[98:101], v[106:109], v[52:55]
	v_mfma_f32_16x16x32_bf16 v[142:145], v[142:145], v[106:109], v[56:59]
	v_mfma_f32_16x16x32_bf16 v[106:109], v[162:165], v[106:109], v[60:63]
	ds_read_b128 v[162:165], v118 offset:49664
	ds_read_b128 v[32:35], v111 offset:32768
	ds_read_b128 v[36:39], v111 offset:34816
	ds_read_b128 v[182:185], v118 offset:53760
	s_waitcnt lgkmcnt(2)
	v_mfma_f32_16x16x32_bf16 v[52:55], v[178:181], v[32:35], v[0:3]
	s_nop 2
	ds_read_b128 v[0:3], v118 offset:53248
	v_mfma_f32_16x16x32_bf16 v[56:59], v[162:165], v[32:35], v[4:7]
	s_nop 2
	ds_read_b128 v[4:7], v111 offset:36864
	ds_read_b128 v[186:189], v111 offset:38912
	s_waitcnt vmcnt(0)
	s_waitcnt lgkmcnt(0)
	v_mfma_f32_16x16x32_bf16 v[60:63], v[0:3], v[32:35], v[8:11]
	s_barrier
	v_mfma_f32_16x16x32_bf16 v[48:51], v[182:185], v[32:35], v[12:15]
	v_mfma_f32_16x16x32_bf16 v[44:47], v[178:181], v[36:39], v[16:19]
	v_mfma_f32_16x16x32_bf16 v[40:43], v[162:165], v[36:39], v[20:23]
	v_mfma_f32_16x16x32_bf16 v[32:35], v[0:3], v[36:39], v[24:27]
	v_mfma_f32_16x16x32_bf16 v[24:27], v[182:185], v[36:39], v[28:31]
	v_mfma_f32_16x16x32_bf16 v[36:39], v[178:181], v[4:7], v[166:169]
	v_mfma_f32_16x16x32_bf16 v[28:31], v[162:165], v[4:7], v[170:173]
	v_mfma_f32_16x16x32_bf16 v[20:23], v[0:3], v[4:7], v[174:177]
	v_mfma_f32_16x16x32_bf16 v[16:19], v[182:185], v[4:7], v[102:105]
	v_mfma_f32_16x16x32_bf16 v[12:15], v[178:181], v[186:189], v[94:97]
	v_mfma_f32_16x16x32_bf16 v[8:11], v[162:165], v[186:189], v[98:101]
	v_mfma_f32_16x16x32_bf16 v[4:7], v[0:3], v[186:189], v[142:145]
	v_mfma_f32_16x16x32_bf16 v[0:3], v[182:185], v[186:189], v[106:109]
	s_cbranch_scc0 .LBB0_454
	s_and_b32 s12, s16, 7
	s_lshl_b32 s12, s12, 3
	s_bfe_u32 s13, s16, 0x30003
	s_or_b32 s12, s12, s13
	s_and_b32 s13, s16, 0xffffffc0
	s_or_b32 s13, s12, s13
	s_ashr_i32 s1, s13, 31
	s_lshr_b32 s1, s1, 29
	s_add_i32 s1, s13, s1
	s_lshl_b32 s5, s1, 4
	s_and_b32 s8, s5, 0xffffff80
	s_and_b32 s1, s1, 0x1fffff8
	s_sub_i32 s1, s13, s1
	s_ashr_i32 s9, s8, 31
	s_lshl_b32 s10, s1, 7
	s_lshl_b64 s[8:9], s[8:9], 11
	v_readlane_b32 s12, v245, 60
	v_readlane_b32 s13, v245, 61
	s_add_u32 s8, s12, s8
	s_addc_u32 s9, s13, s9
	s_ashr_i32 s11, s10, 31
	s_lshl_b64 s[10:11], s[10:11], 11
	s_add_u32 s10, s14, s10
	v_readfirstlane_b32 s1, v149
	s_addc_u32 s11, s15, s11
	s_mov_b32 m0, s1
	v_readfirstlane_b32 s1, v119
	global_load_lds_dwordx4 v126, s[8:9]
	v_lshl_add_u64 v[94:95], v[64:65], 1, s[10:11]
	s_mov_b32 m0, s1
	v_readfirstlane_b32 s1, v120
	global_load_lds_dwordx4 v[94:95], off
	s_mov_b32 m0, s1
	v_readfirstlane_b32 s1, v121
	global_load_lds_dwordx4 v127, s[8:9]
	v_lshl_add_u64 v[94:95], v[66:67], 1, s[10:11]
	s_mov_b32 m0, s1
	v_readfirstlane_b32 s1, v122
	global_load_lds_dwordx4 v[94:95], off
	s_mov_b32 m0, s1
	v_readfirstlane_b32 s1, v123
	global_load_lds_dwordx4 v128, s[8:9]
	v_lshl_add_u64 v[94:95], v[68:69], 1, s[10:11]
	s_mov_b32 m0, s1
	v_readfirstlane_b32 s1, v124
	global_load_lds_dwordx4 v[94:95], off
	s_mov_b32 m0, s1
	v_readfirstlane_b32 s1, v125
	global_load_lds_dwordx4 v129, s[8:9]
	v_lshl_add_u64 v[94:95], v[70:71], 1, s[10:11]
	s_mov_b32 m0, s1
	s_nop 0
	global_load_lds_dwordx4 v[94:95], off
	s_branch .LBB0_454

; template <class Epi>
; __device__ __forceinline__ void gemm_tile(const bf16_t* __restrict__ A, const bf16_t* __restrict__ Bt, int K, int row0, int col0, const Epi& epi, char* smem,
;                                           bool prefetched, bool nvalid, int nrow0, int ncol0) {
;     ...
;     const bf16_t* pA = A + (size_t)row0 * K;
;     const bf16_t* pB = Bt + (size_t)col0 * K;
;     ...
;     int offA[4][2], offB[4][2];
; #pragma unroll
;     for (int m = 0; m < 4; ++m)
; #pragma unroll
;         for (int ks = 0; ks < 2; ++ks) { const int cx = ((ks * 4 + fq) ^ ((fr >> 1) & 7)) * 16;
;             offA[m][ks] = (wr * 64 + m * 16 + fr) * 128 + cx;
;             offB[m][ks] = TILE_B + (wc * 64 + (m >> 1) * 32 + 8 * (fr >> 2) + 4 * (m & 1) + (fr & 3)) * 128 + cx; }
;     if (prefetched) {
;         if (Epi::STAGED) asm volatile("s_waitcnt vmcnt(8)" ::: "memory");
;         else asm volatile("s_waitcnt vmcnt(0)" ::: "memory");
;     } else {
;         GLDS_STAGE(0, pA, pB, 0);
;         asm volatile("s_waitcnt vmcnt(0)" ::: "memory");
; template <class Epi>
; __device__ __forceinline__ void gemm_phase(const bf16_t* A, const bf16_t* Bt, int M, int N, int K, const Epi& epi, char* smem) {
;     ...
;     for (int i = blockIdx.x; i < ntiles; i += G) {
;         const int j = i + G; const bool nv = j < ntiles;
;         gemm_tile(A, Bt, K, (i / nN) << 7, (i % nN) << 7, epi, smem, pre, nv, (j / nN) << 7, (j % nN) << 7);
.LBB0_614:
	s_and_b32 s2, s16, 7
	s_lshl_b32 s2, s2, 3
	s_bfe_u32 s3, s16, 0x30003
	s_or_b32 s2, s2, s3
	s_and_b32 s3, s16, 0xffffffc0
	s_or_b32 s3, s2, s3
	s_ashr_i32 s0, s3, 31
	s_lshr_b32 s0, s0, 29
	s_add_i32 s1, s3, s0
	s_lshl_b32 s0, s1, 4
	s_and_b32 s1, s1, 0x1fffff8
	s_sub_i32 s1, s3, s1
	s_and_b32 s0, s0, 0xffffff80
	s_lshl_b32 s2, s1, 7
	s_ashr_i32 s1, s0, 31
	s_ashr_i32 s3, s2, 31
	s_lshl_b64 s[8:9], s[0:1], 13
	s_lshl_b64 s[6:7], s[2:3], 13
	s_mov_b64 s[12:13], -1
	s_and_b64 vcc, exec, s[10:11]
	s_cbranch_vccnz .LBB0_616
	v_readlane_b32 s10, v245, 55
	v_readlane_b32 s11, v245, 56
	s_add_u32 s10, s10, s8
	s_addc_u32 s11, s11, s9
	s_add_u32 s12, s14, s6
	v_readfirstlane_b32 s1, v149
	s_addc_u32 s13, s15, s7
	s_mov_b32 m0, s1
	v_readfirstlane_b32 s1, v118
	global_load_lds_dwordx4 v125, s[10:11]
	v_lshl_add_u64 v[0:1], v[64:65], 1, s[12:13]
	s_mov_b32 m0, s1
	v_readfirstlane_b32 s1, v119
	global_load_lds_dwordx4 v[0:1], off
	s_mov_b32 m0, s1
	v_readfirstlane_b32 s1, v120
	global_load_lds_dwordx4 v126, s[10:11]
	v_lshl_add_u64 v[0:1], v[66:67], 1, s[12:13]
	s_mov_b32 m0, s1
	v_readfirstlane_b32 s1, v121
	global_load_lds_dwordx4 v[0:1], off
	s_mov_b32 m0, s1
	v_readfirstlane_b32 s1, v122
	global_load_lds_dwordx4 v127, s[10:11]
	v_lshl_add_u64 v[0:1], v[68:69], 1, s[12:13]
	s_mov_b32 m0, s1
	v_readfirstlane_b32 s1, v123
	global_load_lds_dwordx4 v[0:1], off
	s_mov_b32 m0, s1
	v_readfirstlane_b32 s1, v124
	global_load_lds_dwordx4 v128, s[10:11]
	v_lshl_add_u64 v[0:1], v[70:71], 1, s[12:13]
	s_mov_b32 m0, s1
	s_mov_b64 s[12:13], 0
	global_load_lds_dwordx4 v[0:1], off
	s_waitcnt vmcnt(0)

; __device__ __forceinline__ f32x4 mfma16(bf16x8 a, bf16x8 b, f32x4 c) { return __builtin_amdgcn_mfma_f32_16x16x32_bf16(a, b, c, 0, 0, 0); }
; template <class Epi>
; __device__ __forceinline__ void gemm_tile(const bf16_t* __restrict__ A, const bf16_t* __restrict__ Bt, int K, int row0, int col0, const Epi& epi, char* smem,
;                                           bool prefetched, bool nvalid, int nrow0, int ncol0) {
;     ...
; #pragma unroll
;         for (int ks = 0; ks < 2; ++ks) {
;             bf16x8 a[4], b[4];
; #pragma unroll
;             for (int m = 0; m < 4; ++m) a[m] = *(const bf16x8*)(cb + offA[m][ks]);
; #pragma unroll
;             for (int n = 0; n < 4; ++n) b[n] = *(const bf16x8*)(cb + offB[n][ks]);
; #pragma unroll
;             for (int m = 0; m < 4; ++m)
; #pragma unroll
;                 for (int n = 0; n < 4; ++n) acc[m][n] = mfma16(b[n], a[m], acc[m][n]);
;         }
;         asm volatile("s_waitcnt vmcnt(0)" ::: "memory");
;         __syncthreads();
;     }
;     if (nvalid) { const bf16_t* qA = A + (size_t)nrow0 * K; const bf16_t* qB = Bt + (size_t)ncol0 * K; GLDS_STAGE(0, qA, qB, 0); }
; template <class Epi>
; __device__ __forceinline__ void gemm_phase(const bf16_t* A, const bf16_t* Bt, int M, int N, int K, const Epi& epi, char* smem) {
;     ...
;     for (int i = blockIdx.x; i < ntiles; i += G) {
;         const int j = i + G; const bool nv = j < ntiles;
;         gemm_tile(A, Bt, K, (i / nN) << 7, (i % nN) << 7, epi, smem, pre, nv, (j / nN) << 7, (j % nN) << 7);
.Lgk_tail_619:
	v_mfma_f32_16x16x32_bf16 v[32:35], v[142:145], v[246:249], v[32:35]
	v_mfma_f32_16x16x32_bf16 v[36:39], v[162:165], v[246:249], v[36:39]
	v_mfma_f32_16x16x32_bf16 v[40:43], v[166:169], v[246:249], v[40:43]
	v_mfma_f32_16x16x32_bf16 v[44:47], v[170:173], v[246:249], v[44:47]
	v_mfma_f32_16x16x32_bf16 v[48:51], v[142:145], v[250:253], v[48:51]
	v_mfma_f32_16x16x32_bf16 v[52:55], v[162:165], v[250:253], v[52:55]
	v_mfma_f32_16x16x32_bf16 v[56:59], v[166:169], v[250:253], v[56:59]
	v_mfma_f32_16x16x32_bf16 v[60:63], v[170:173], v[250:253], v[60:63]
	ds_read_b128 v[92:95], v110 offset:49152
	ds_read_b128 v[96:99], v110 offset:49664
	ds_read_b128 v[100:103], v108 offset:32768
	ds_read_b128 v[104:107], v108 offset:34816
	ds_read_b128 v[142:145], v110 offset:53248
	ds_read_b128 v[162:165], v110 offset:53760
	s_add_i32 s16, s16, s58
	s_waitcnt lgkmcnt(3)
	v_mfma_f32_16x16x32_bf16 v[0:3], v[92:95], v[100:103], v[0:3]
	s_cmpk_gt_i32 s16, 0x7ff
	s_cselect_b64 s[6:7], -1, 0
	s_cmpk_lt_i32 s16, 0x800
	v_mfma_f32_16x16x32_bf16 v[4:7], v[96:99], v[100:103], v[4:7]
	s_waitcnt lgkmcnt(1)
	v_mfma_f32_16x16x32_bf16 v[8:11], v[142:145], v[100:103], v[8:11]
	s_waitcnt lgkmcnt(0)
	v_mfma_f32_16x16x32_bf16 v[12:15], v[162:165], v[100:103], v[12:15]
	v_mfma_f32_16x16x32_bf16 v[16:19], v[92:95], v[104:107], v[16:19]
	v_mfma_f32_16x16x32_bf16 v[20:23], v[96:99], v[104:107], v[20:23]
	v_mfma_f32_16x16x32_bf16 v[24:27], v[142:145], v[104:107], v[24:27]
	v_mfma_f32_16x16x32_bf16 v[28:31], v[162:165], v[104:107], v[28:31]
	ds_read_b128 v[100:103], v108 offset:36864
	ds_read_b128 v[104:107], v108 offset:38912
	ds_read_b128 v[178:181], v111 offset:49152
	s_waitcnt lgkmcnt(2)
	v_mfma_f32_16x16x32_bf16 v[166:169], v[92:95], v[100:103], v[32:35]
	v_mfma_f32_16x16x32_bf16 v[170:173], v[96:99], v[100:103], v[36:39]
	v_mfma_f32_16x16x32_bf16 v[174:177], v[142:145], v[100:103], v[40:43]
	v_mfma_f32_16x16x32_bf16 v[100:103], v[162:165], v[100:103], v[44:47]
	s_waitcnt lgkmcnt(1)
	v_mfma_f32_16x16x32_bf16 v[92:95], v[92:95], v[104:107], v[48:51]
	v_mfma_f32_16x16x32_bf16 v[96:99], v[96:99], v[104:107], v[52:55]
	v_mfma_f32_16x16x32_bf16 v[142:145], v[142:145], v[104:107], v[56:59]
	v_mfma_f32_16x16x32_bf16 v[104:107], v[162:165], v[104:107], v[60:63]
	ds_read_b128 v[162:165], v111 offset:49664
	ds_read_b128 v[32:35], v109 offset:32768
	ds_read_b128 v[36:39], v109 offset:34816
	ds_read_b128 v[182:185], v111 offset:53760
	s_waitcnt lgkmcnt(2)
	v_mfma_f32_16x16x32_bf16 v[52:55], v[178:181], v[32:35], v[0:3]
	s_nop 2
	ds_read_b128 v[0:3], v111 offset:53248
	v_mfma_f32_16x16x32_bf16 v[56:59], v[162:165], v[32:35], v[4:7]
	s_nop 2
	ds_read_b128 v[4:7], v109 offset:36864
	ds_read_b128 v[186:189], v109 offset:38912
	s_waitcnt vmcnt(0)
	s_waitcnt lgkmcnt(0)
	v_mfma_f32_16x16x32_bf16 v[60:63], v[0:3], v[32:35], v[8:11]
	s_barrier
	v_mfma_f32_16x16x32_bf16 v[48:51], v[182:185], v[32:35], v[12:15]
	v_mfma_f32_16x16x32_bf16 v[44:47], v[178:181], v[36:39], v[16:19]
	v_mfma_f32_16x16x32_bf16 v[40:43], v[162:165], v[36:39], v[20:23]
	v_mfma_f32_16x16x32_bf16 v[32:35], v[0:3], v[36:39], v[24:27]
	v_mfma_f32_16x16x32_bf16 v[24:27], v[182:185], v[36:39], v[28:31]
	v_mfma_f32_16x16x32_bf16 v[36:39], v[178:181], v[4:7], v[166:169]
	v_mfma_f32_16x16x32_bf16 v[28:31], v[162:165], v[4:7], v[170:173]
	v_mfma_f32_16x16x32_bf16 v[20:23], v[0:3], v[4:7], v[174:177]
	v_mfma_f32_16x16x32_bf16 v[16:19], v[182:185], v[4:7], v[100:103]
	v_mfma_f32_16x16x32_bf16 v[12:15], v[178:181], v[186:189], v[92:95]
	v_mfma_f32_16x16x32_bf16 v[8:11], v[162:165], v[186:189], v[96:99]
	v_mfma_f32_16x16x32_bf16 v[4:7], v[0:3], v[186:189], v[142:145]
	v_mfma_f32_16x16x32_bf16 v[0:3], v[182:185], v[186:189], v[104:107]
	s_cbranch_scc0 .LBB0_613
	s_and_b32 s12, s16, 7
	s_lshl_b32 s12, s12, 3
	s_bfe_u32 s13, s16, 0x30003
	s_or_b32 s12, s12, s13
	s_and_b32 s13, s16, 0xffffffc0
	s_or_b32 s13, s12, s13
	s_ashr_i32 s1, s13, 31
	s_lshr_b32 s1, s1, 29
	s_add_i32 s1, s13, s1
	s_lshl_b32 s3, s1, 4
	s_and_b32 s8, s3, 0xffffff80
	s_and_b32 s1, s1, 0x1fffff8
	s_sub_i32 s1, s13, s1
	s_ashr_i32 s9, s8, 31
	s_lshl_b32 s10, s1, 7
	s_lshl_b64 s[8:9], s[8:9], 13
	v_readlane_b32 s12, v245, 55
	v_readlane_b32 s13, v245, 56
	s_add_u32 s8, s12, s8
	s_addc_u32 s9, s13, s9
	s_ashr_i32 s11, s10, 31
	s_lshl_b64 s[10:11], s[10:11], 13
	s_add_u32 s10, s14, s10
	v_readfirstlane_b32 s1, v149
	s_addc_u32 s11, s15, s11
	s_mov_b32 m0, s1
	v_readfirstlane_b32 s1, v118
	global_load_lds_dwordx4 v125, s[8:9]
	v_lshl_add_u64 v[92:93], v[64:65], 1, s[10:11]
	s_mov_b32 m0, s1
	v_readfirstlane_b32 s1, v119
	global_load_lds_dwordx4 v[92:93], off
	s_mov_b32 m0, s1
	v_readfirstlane_b32 s1, v120
	global_load_lds_dwordx4 v126, s[8:9]
	v_lshl_add_u64 v[92:93], v[66:67], 1, s[10:11]
	s_mov_b32 m0, s1
	v_readfirstlane_b32 s1, v121
	global_load_lds_dwordx4 v[92:93], off
	s_mov_b32 m0, s1
	v_readfirstlane_b32 s1, v122
	global_load_lds_dwordx4 v127, s[8:9]
	v_lshl_add_u64 v[92:93], v[68:69], 1, s[10:11]
	s_mov_b32 m0, s1
	v_readfirstlane_b32 s1, v123
	global_load_lds_dwordx4 v[92:93], off
	s_mov_b32 m0, s1
	v_readfirstlane_b32 s1, v124
	global_load_lds_dwordx4 v128, s[8:9]
	v_lshl_add_u64 v[92:93], v[70:71], 1, s[10:11]
	s_mov_b32 m0, s1
	s_nop 0
	global_load_lds_dwordx4 v[92:93], off
	s_branch .LBB0_613

; template <class Epi>
; __device__ __forceinline__ void gemm_tile(const bf16_t* __restrict__ A, const bf16_t* __restrict__ Bt, int K, int row0, int col0, const Epi& epi, char* smem,
;                                           bool prefetched, bool nvalid, int nrow0, int ncol0) {
;     ...
;     const bf16_t* pA = A + (size_t)row0 * K;
;     const bf16_t* pB = Bt + (size_t)col0 * K;
;     ...
;     int offA[4][2], offB[4][2];
; #pragma unroll
;     for (int m = 0; m < 4; ++m)
; #pragma unroll
;         for (int ks = 0; ks < 2; ++ks) { const int cx = ((ks * 4 + fq) ^ ((fr >> 1) & 7)) * 16;
;             offA[m][ks] = (wr * 64 + m * 16 + fr) * 128 + cx;
;             offB[m][ks] = TILE_B + (wc * 64 + (m >> 1) * 32 + 8 * (fr >> 2) + 4 * (m & 1) + (fr & 3)) * 128 + cx; }
;     if (prefetched) {
;         if (Epi::STAGED) asm volatile("s_waitcnt vmcnt(8)" ::: "memory");
;         else asm volatile("s_waitcnt vmcnt(0)" ::: "memory");
;     } else {
;         GLDS_STAGE(0, pA, pB, 0);
;         asm volatile("s_waitcnt vmcnt(0)" ::: "memory");
; template <class Epi>
; __device__ __forceinline__ void gemm_phase(const bf16_t* A, const bf16_t* Bt, int M, int N, int K, const Epi& epi, char* smem) {
;     ...
;     for (int i = blockIdx.x; i < ntiles; i += G) {
;         const int j = i + G; const bool nv = j < ntiles;
;         gemm_tile(A, Bt, K, (i / nN) << 7, (i % nN) << 7, epi, smem, pre, nv, (j / nN) << 7, (j % nN) << 7);
.LBB0_890:
	s_and_b32 s2, s16, 7
	s_lshl_b32 s2, s2, 3
	s_bfe_u32 s3, s16, 0x30003
	s_or_b32 s2, s2, s3
	s_and_b32 s3, s16, 0xffffffc0
	s_or_b32 s3, s2, s3
	s_ashr_i32 s0, s3, 31
	s_lshr_b32 s0, s0, 29
	s_add_i32 s1, s3, s0
	s_lshl_b32 s0, s1, 4
	s_and_b32 s1, s1, 0x1fffff8
	s_sub_i32 s1, s3, s1
	s_and_b32 s0, s0, 0xffffff80
	s_lshl_b32 s2, s1, 7
	s_ashr_i32 s1, s0, 31
	s_ashr_i32 s3, s2, 31
	s_lshl_b64 s[8:9], s[0:1], 11
	s_lshl_b64 s[6:7], s[2:3], 11
	s_mov_b64 s[12:13], -1
	s_and_b64 vcc, exec, s[10:11]
	s_cbranch_vccnz .LBB0_892
	v_readlane_b32 s10, v245, 60
	v_readlane_b32 s11, v245, 61
	s_add_u32 s10, s10, s8
	s_addc_u32 s11, s11, s9
	s_add_u32 s12, s14, s6
	v_readfirstlane_b32 s1, v149
	s_addc_u32 s13, s15, s7
	s_mov_b32 m0, s1
	v_readfirstlane_b32 s1, v118
	global_load_lds_dwordx4 v125, s[10:11]
	v_lshl_add_u64 v[0:1], v[64:65], 1, s[12:13]
	s_mov_b32 m0, s1
	v_readfirstlane_b32 s1, v119
	global_load_lds_dwordx4 v[0:1], off
	s_mov_b32 m0, s1
	v_readfirstlane_b32 s1, v120
	global_load_lds_dwordx4 v126, s[10:11]
	v_lshl_add_u64 v[0:1], v[66:67], 1, s[12:13]
	s_mov_b32 m0, s1
	v_readfirstlane_b32 s1, v121
	global_load_lds_dwordx4 v[0:1], off
	s_mov_b32 m0, s1
	v_readfirstlane_b32 s1, v122
	global_load_lds_dwordx4 v127, s[10:11]
	v_lshl_add_u64 v[0:1], v[68:69], 1, s[12:13]
	s_mov_b32 m0, s1
	v_readfirstlane_b32 s1, v123
	global_load_lds_dwordx4 v[0:1], off
	s_mov_b32 m0, s1
	v_readfirstlane_b32 s1, v124
	global_load_lds_dwordx4 v130, s[10:11]
	v_lshl_add_u64 v[0:1], v[70:71], 1, s[12:13]
	s_mov_b32 m0, s1
	s_mov_b64 s[12:13], 0
	global_load_lds_dwordx4 v[0:1], off
	s_waitcnt vmcnt(0)

; __device__ __forceinline__ f32x4 mfma16(bf16x8 a, bf16x8 b, f32x4 c) { return __builtin_amdgcn_mfma_f32_16x16x32_bf16(a, b, c, 0, 0, 0); }
; template <class Epi>
; __device__ __forceinline__ void gemm_tile(const bf16_t* __restrict__ A, const bf16_t* __restrict__ Bt, int K, int row0, int col0, const Epi& epi, char* smem,
;                                           bool prefetched, bool nvalid, int nrow0, int ncol0) {
;     ...
; #pragma unroll
;         for (int ks = 0; ks < 2; ++ks) {
;             bf16x8 a[4], b[4];
; #pragma unroll
;             for (int m = 0; m < 4; ++m) a[m] = *(const bf16x8*)(cb + offA[m][ks]);
; #pragma unroll
;             for (int n = 0; n < 4; ++n) b[n] = *(const bf16x8*)(cb + offB[n][ks]);
; #pragma unroll
;             for (int m = 0; m < 4; ++m)
; #pragma unroll
;                 for (int n = 0; n < 4; ++n) acc[m][n] = mfma16(b[n], a[m], acc[m][n]);
;         }
;         asm volatile("s_waitcnt vmcnt(0)" ::: "memory");
;         __syncthreads();
;     }
;     if (nvalid) { const bf16_t* qA = A + (size_t)nrow0 * K; const bf16_t* qB = Bt + (size_t)ncol0 * K; GLDS_STAGE(0, qA, qB, 0); }
; template <class Epi>
; __device__ __forceinline__ void gemm_phase(const bf16_t* A, const bf16_t* Bt, int M, int N, int K, const Epi& epi, char* smem) {
;     ...
;     for (int i = blockIdx.x; i < ntiles; i += G) {
;         const int j = i + G; const bool nv = j < ntiles;
;         gemm_tile(A, Bt, K, (i / nN) << 7, (i % nN) << 7, epi, smem, pre, nv, (j / nN) << 7, (j % nN) << 7);
.Lgk_tail_895:
	v_mfma_f32_16x16x32_bf16 v[32:35], v[132:135], v[246:249], v[32:35]
	v_mfma_f32_16x16x32_bf16 v[36:39], v[136:139], v[246:249], v[36:39]
	v_mfma_f32_16x16x32_bf16 v[40:43], v[140:143], v[246:249], v[40:43]
	v_mfma_f32_16x16x32_bf16 v[44:47], v[170:173], v[246:249], v[44:47]
	v_mfma_f32_16x16x32_bf16 v[48:51], v[132:135], v[250:253], v[48:51]
	v_mfma_f32_16x16x32_bf16 v[52:55], v[136:139], v[250:253], v[52:55]
	v_mfma_f32_16x16x32_bf16 v[56:59], v[140:143], v[250:253], v[56:59]
	v_mfma_f32_16x16x32_bf16 v[60:63], v[170:173], v[250:253], v[60:63]
	ds_read_b128 v[92:95], v110 offset:49152
	ds_read_b128 v[96:99], v110 offset:49664
	ds_read_b128 v[100:103], v108 offset:32768
	ds_read_b128 v[104:107], v108 offset:34816
	ds_read_b128 v[132:135], v110 offset:53248
	ds_read_b128 v[136:139], v110 offset:53760
	s_add_i32 s16, s16, s58
	s_waitcnt lgkmcnt(3)
	v_mfma_f32_16x16x32_bf16 v[0:3], v[92:95], v[100:103], v[0:3]
	s_cmpk_gt_i32 s16, 0x7ff
	s_cselect_b64 s[6:7], -1, 0
	s_cmpk_lt_i32 s16, 0x800
	v_mfma_f32_16x16x32_bf16 v[4:7], v[96:99], v[100:103], v[4:7]
	s_waitcnt lgkmcnt(1)
	v_mfma_f32_16x16x32_bf16 v[8:11], v[132:135], v[100:103], v[8:11]
	s_waitcnt lgkmcnt(0)
	v_mfma_f32_16x16x32_bf16 v[12:15], v[136:139], v[100:103], v[12:15]
	v_mfma_f32_16x16x32_bf16 v[16:19], v[92:95], v[104:107], v[16:19]
	v_mfma_f32_16x16x32_bf16 v[20:23], v[96:99], v[104:107], v[20:23]
	v_mfma_f32_16x16x32_bf16 v[24:27], v[132:135], v[104:107], v[24:27]
	v_mfma_f32_16x16x32_bf16 v[28:31], v[136:139], v[104:107], v[28:31]
	ds_read_b128 v[100:103], v108 offset:36864
	ds_read_b128 v[104:107], v108 offset:38912
	ds_read_b128 v[178:181], v111 offset:49152
	s_waitcnt lgkmcnt(2)
	v_mfma_f32_16x16x32_bf16 v[140:143], v[92:95], v[100:103], v[32:35]
	v_mfma_f32_16x16x32_bf16 v[170:173], v[96:99], v[100:103], v[36:39]
	v_mfma_f32_16x16x32_bf16 v[174:177], v[132:135], v[100:103], v[40:43]
	v_mfma_f32_16x16x32_bf16 v[100:103], v[136:139], v[100:103], v[44:47]
	s_waitcnt lgkmcnt(1)
	v_mfma_f32_16x16x32_bf16 v[92:95], v[92:95], v[104:107], v[48:51]
	v_mfma_f32_16x16x32_bf16 v[96:99], v[96:99], v[104:107], v[52:55]
	v_mfma_f32_16x16x32_bf16 v[132:135], v[132:135], v[104:107], v[56:59]
	v_mfma_f32_16x16x32_bf16 v[104:107], v[136:139], v[104:107], v[60:63]
	ds_read_b128 v[136:139], v111 offset:49664
	ds_read_b128 v[32:35], v109 offset:32768
	ds_read_b128 v[36:39], v109 offset:34816
	ds_read_b128 v[182:185], v111 offset:53760
	s_waitcnt lgkmcnt(2)
	v_mfma_f32_16x16x32_bf16 v[52:55], v[178:181], v[32:35], v[0:3]
	s_nop 2
	ds_read_b128 v[0:3], v111 offset:53248
	v_mfma_f32_16x16x32_bf16 v[56:59], v[136:139], v[32:35], v[4:7]
	s_nop 2
	ds_read_b128 v[4:7], v109 offset:36864
	ds_read_b128 v[186:189], v109 offset:38912
	s_waitcnt vmcnt(0)
	s_waitcnt lgkmcnt(0)
	v_mfma_f32_16x16x32_bf16 v[60:63], v[0:3], v[32:35], v[8:11]
	s_barrier
	v_mfma_f32_16x16x32_bf16 v[48:51], v[182:185], v[32:35], v[12:15]
	v_mfma_f32_16x16x32_bf16 v[44:47], v[178:181], v[36:39], v[16:19]
	v_mfma_f32_16x16x32_bf16 v[40:43], v[136:139], v[36:39], v[20:23]
	v_mfma_f32_16x16x32_bf16 v[32:35], v[0:3], v[36:39], v[24:27]
	v_mfma_f32_16x16x32_bf16 v[24:27], v[182:185], v[36:39], v[28:31]
	v_mfma_f32_16x16x32_bf16 v[36:39], v[178:181], v[4:7], v[140:143]
	v_mfma_f32_16x16x32_bf16 v[28:31], v[136:139], v[4:7], v[170:173]
	v_mfma_f32_16x16x32_bf16 v[20:23], v[0:3], v[4:7], v[174:177]
	v_mfma_f32_16x16x32_bf16 v[16:19], v[182:185], v[4:7], v[100:103]
	v_mfma_f32_16x16x32_bf16 v[12:15], v[178:181], v[186:189], v[92:95]
	v_mfma_f32_16x16x32_bf16 v[8:11], v[136:139], v[186:189], v[96:99]
	v_mfma_f32_16x16x32_bf16 v[4:7], v[0:3], v[186:189], v[132:135]
	v_mfma_f32_16x16x32_bf16 v[0:3], v[182:185], v[186:189], v[104:107]
	s_cbranch_scc0 .LBB0_889
	s_and_b32 s12, s16, 7
	s_lshl_b32 s12, s12, 3
	s_bfe_u32 s13, s16, 0x30003
	s_or_b32 s12, s12, s13
	s_and_b32 s13, s16, 0xffffffc0
	s_or_b32 s13, s12, s13
	s_ashr_i32 s1, s13, 31
	s_lshr_b32 s1, s1, 29
	s_add_i32 s1, s13, s1
	s_lshl_b32 s3, s1, 4
	s_and_b32 s8, s3, 0xffffff80
	s_and_b32 s1, s1, 0x1fffff8
	s_sub_i32 s1, s13, s1
	s_ashr_i32 s9, s8, 31
	s_lshl_b32 s10, s1, 7
	s_lshl_b64 s[8:9], s[8:9], 11
	v_readlane_b32 s12, v245, 60
	v_readlane_b32 s13, v245, 61
	s_add_u32 s8, s12, s8
	s_addc_u32 s9, s13, s9
	s_ashr_i32 s11, s10, 31
	s_lshl_b64 s[10:11], s[10:11], 11
	s_add_u32 s10, s14, s10
	v_readfirstlane_b32 s1, v149
	s_addc_u32 s11, s15, s11
	s_mov_b32 m0, s1
	v_readfirstlane_b32 s1, v118
	global_load_lds_dwordx4 v125, s[8:9]
	v_lshl_add_u64 v[92:93], v[64:65], 1, s[10:11]
	s_mov_b32 m0, s1
	v_readfirstlane_b32 s1, v119
	global_load_lds_dwordx4 v[92:93], off
	s_mov_b32 m0, s1
	v_readfirstlane_b32 s1, v120
	global_load_lds_dwordx4 v126, s[8:9]
	v_lshl_add_u64 v[92:93], v[66:67], 1, s[10:11]
	s_mov_b32 m0, s1
	v_readfirstlane_b32 s1, v121
	global_load_lds_dwordx4 v[92:93], off
	s_mov_b32 m0, s1
	v_readfirstlane_b32 s1, v122
	global_load_lds_dwordx4 v127, s[8:9]
	v_lshl_add_u64 v[92:93], v[68:69], 1, s[10:11]
	s_mov_b32 m0, s1
	v_readfirstlane_b32 s1, v123
	global_load_lds_dwordx4 v[92:93], off
	s_mov_b32 m0, s1
	v_readfirstlane_b32 s1, v124
	global_load_lds_dwordx4 v130, s[8:9]
	v_lshl_add_u64 v[92:93], v[70:71], 1, s[10:11]
	s_mov_b32 m0, s1
	s_nop 0
	global_load_lds_dwordx4 v[92:93], off
	s_branch .LBB0_889

; template <class Epi>
; __device__ __forceinline__ void gemm_tile(const bf16_t* __restrict__ A, const bf16_t* __restrict__ Bt, int K, int row0, int col0, const Epi& epi, char* smem,
;                                           bool prefetched, bool nvalid, int nrow0, int ncol0) {
;     ...
;     const bf16_t* pA = A + (size_t)row0 * K;
;     const bf16_t* pB = Bt + (size_t)col0 * K;
;     ...
;     int offA[4][2], offB[4][2];
; #pragma unroll
;     for (int m = 0; m < 4; ++m)
; #pragma unroll
;         for (int ks = 0; ks < 2; ++ks) { const int cx = ((ks * 4 + fq) ^ ((fr >> 1) & 7)) * 16;
;             offA[m][ks] = (wr * 64 + m * 16 + fr) * 128 + cx;
;             offB[m][ks] = TILE_B + (wc * 64 + (m >> 1) * 32 + 8 * (fr >> 2) + 4 * (m & 1) + (fr & 3)) * 128 + cx; }
;     if (prefetched) {
;         if (Epi::STAGED) asm volatile("s_waitcnt vmcnt(8)" ::: "memory");
;         else asm volatile("s_waitcnt vmcnt(0)" ::: "memory");
;     } else {
;         GLDS_STAGE(0, pA, pB, 0);
;         asm volatile("s_waitcnt vmcnt(0)" ::: "memory");
; template <class Epi>
; __device__ __forceinline__ void gemm_phase(const bf16_t* A, const bf16_t* Bt, int M, int N, int K, const Epi& epi, char* smem) {
;     ...
;     for (int i = blockIdx.x; i < ntiles; i += G) {
;         const int j = i + G; const bool nv = j < ntiles;
;         gemm_tile(A, Bt, K, (i / nN) << 7, (i % nN) << 7, epi, smem, pre, nv, (j / nN) << 7, (j % nN) << 7);
.LBB0_1049:
	s_and_b32 s2, s16, 7
	s_lshl_b32 s2, s2, 3
	s_bfe_u32 s3, s16, 0x30003
	s_or_b32 s2, s2, s3
	s_and_b32 s3, s16, 0xffffffc0
	s_or_b32 s3, s2, s3
	s_ashr_i32 s0, s3, 31
	s_lshr_b32 s0, s0, 29
	s_add_i32 s1, s3, s0
	s_lshl_b32 s0, s1, 4
	s_and_b32 s1, s1, 0x1fffff8
	s_sub_i32 s1, s3, s1
	s_and_b32 s0, s0, 0xffffff80
	s_lshl_b32 s2, s1, 7
	s_ashr_i32 s1, s0, 31
	s_ashr_i32 s3, s2, 31
	s_lshl_b64 s[6:7], s[0:1], 13
	s_lshl_b64 s[4:5], s[2:3], 13
	s_mov_b64 s[10:11], -1
	s_and_b64 vcc, exec, s[8:9]
	s_cbranch_vccnz .LBB0_1051
	v_readlane_b32 s8, v245, 55
	v_readlane_b32 s9, v245, 56
	s_add_u32 s8, s8, s6
	s_addc_u32 s9, s9, s7
	s_add_u32 s10, s12, s4
	v_readfirstlane_b32 s1, v149
	s_addc_u32 s11, s13, s5
	s_mov_b32 m0, s1
	v_readfirstlane_b32 s1, v114
	global_load_lds_dwordx4 v123, s[8:9]
	v_lshl_add_u64 v[0:1], v[64:65], 1, s[10:11]
	s_mov_b32 m0, s1
	v_readfirstlane_b32 s1, v116
	global_load_lds_dwordx4 v[0:1], off
	s_mov_b32 m0, s1
	v_readfirstlane_b32 s1, v118
	global_load_lds_dwordx4 v124, s[8:9]
	v_lshl_add_u64 v[0:1], v[66:67], 1, s[10:11]
	s_mov_b32 m0, s1
	v_readfirstlane_b32 s1, v119
	global_load_lds_dwordx4 v[0:1], off
	s_mov_b32 m0, s1
	v_readfirstlane_b32 s1, v120
	global_load_lds_dwordx4 v125, s[8:9]
	v_lshl_add_u64 v[0:1], v[68:69], 1, s[10:11]
	s_mov_b32 m0, s1
	v_readfirstlane_b32 s1, v121
	global_load_lds_dwordx4 v[0:1], off
	s_mov_b32 m0, s1
	v_readfirstlane_b32 s1, v122
	global_load_lds_dwordx4 v126, s[8:9]
	v_lshl_add_u64 v[0:1], v[70:71], 1, s[10:11]
	s_mov_b32 m0, s1
	s_mov_b64 s[10:11], 0
	global_load_lds_dwordx4 v[0:1], off
	s_waitcnt vmcnt(0)

; __device__ __forceinline__ f32x4 mfma16(bf16x8 a, bf16x8 b, f32x4 c) { return __builtin_amdgcn_mfma_f32_16x16x32_bf16(a, b, c, 0, 0, 0); }
; template <class Epi>
; __device__ __forceinline__ void gemm_tile(const bf16_t* __restrict__ A, const bf16_t* __restrict__ Bt, int K, int row0, int col0, const Epi& epi, char* smem,
;                                           bool prefetched, bool nvalid, int nrow0, int ncol0) {
;     ...
; #pragma unroll
;         for (int ks = 0; ks < 2; ++ks) {
;             bf16x8 a[4], b[4];
; #pragma unroll
;             for (int m = 0; m < 4; ++m) a[m] = *(const bf16x8*)(cb + offA[m][ks]);
; #pragma unroll
;             for (int n = 0; n < 4; ++n) b[n] = *(const bf16x8*)(cb + offB[n][ks]);
; #pragma unroll
;             for (int m = 0; m < 4; ++m)
; #pragma unroll
;                 for (int n = 0; n < 4; ++n) acc[m][n] = mfma16(b[n], a[m], acc[m][n]);
;         }
;         asm volatile("s_waitcnt vmcnt(0)" ::: "memory");
;         __syncthreads();
;     }
;     if (nvalid) { const bf16_t* qA = A + (size_t)nrow0 * K; const bf16_t* qB = Bt + (size_t)ncol0 * K; GLDS_STAGE(0, qA, qB, 0); }
; template <class Epi>
; __device__ __forceinline__ void gemm_phase(const bf16_t* A, const bf16_t* Bt, int M, int N, int K, const Epi& epi, char* smem) {
;     ...
;     for (int i = blockIdx.x; i < ntiles; i += G) {
;         const int j = i + G; const bool nv = j < ntiles;
;         gemm_tile(A, Bt, K, (i / nN) << 7, (i % nN) << 7, epi, smem, pre, nv, (j / nN) << 7, (j % nN) << 7);
.Lgk_tail_1054:
	v_mfma_f32_16x16x32_bf16 v[32:35], v[128:131], v[246:249], v[32:35]
	v_mfma_f32_16x16x32_bf16 v[36:39], v[132:135], v[246:249], v[36:39]
	v_mfma_f32_16x16x32_bf16 v[40:43], v[136:139], v[246:249], v[40:43]
	v_mfma_f32_16x16x32_bf16 v[44:47], v[140:143], v[246:249], v[44:47]
	v_mfma_f32_16x16x32_bf16 v[48:51], v[128:131], v[250:253], v[48:51]
	v_mfma_f32_16x16x32_bf16 v[52:55], v[132:135], v[250:253], v[52:55]
	v_mfma_f32_16x16x32_bf16 v[56:59], v[136:139], v[250:253], v[56:59]
	v_mfma_f32_16x16x32_bf16 v[60:63], v[140:143], v[250:253], v[60:63]
	ds_read_b128 v[92:95], v110 offset:49152
	ds_read_b128 v[96:99], v110 offset:49664
	ds_read_b128 v[100:103], v108 offset:32768
	ds_read_b128 v[104:107], v108 offset:34816
	ds_read_b128 v[128:131], v110 offset:53248
	ds_read_b128 v[132:135], v110 offset:53760
	s_add_i32 s16, s16, s58
	s_waitcnt lgkmcnt(3)
	v_mfma_f32_16x16x32_bf16 v[0:3], v[92:95], v[100:103], v[0:3]
	s_cmpk_gt_i32 s16, 0x7ff
	s_cselect_b64 s[4:5], -1, 0
	s_cmpk_lt_i32 s16, 0x800
	v_mfma_f32_16x16x32_bf16 v[4:7], v[96:99], v[100:103], v[4:7]
	s_waitcnt lgkmcnt(1)
	v_mfma_f32_16x16x32_bf16 v[8:11], v[128:131], v[100:103], v[8:11]
	s_waitcnt lgkmcnt(0)
	v_mfma_f32_16x16x32_bf16 v[12:15], v[132:135], v[100:103], v[12:15]
	v_mfma_f32_16x16x32_bf16 v[16:19], v[92:95], v[104:107], v[16:19]
	v_mfma_f32_16x16x32_bf16 v[20:23], v[96:99], v[104:107], v[20:23]
	v_mfma_f32_16x16x32_bf16 v[24:27], v[128:131], v[104:107], v[24:27]
	v_mfma_f32_16x16x32_bf16 v[28:31], v[132:135], v[104:107], v[28:31]
	ds_read_b128 v[100:103], v108 offset:36864
	ds_read_b128 v[104:107], v108 offset:38912
	ds_read_b128 v[154:157], v111 offset:49152
	s_waitcnt lgkmcnt(2)
	v_mfma_f32_16x16x32_bf16 v[136:139], v[92:95], v[100:103], v[32:35]
	v_mfma_f32_16x16x32_bf16 v[140:143], v[96:99], v[100:103], v[36:39]
	v_mfma_f32_16x16x32_bf16 v[150:153], v[128:131], v[100:103], v[40:43]
	v_mfma_f32_16x16x32_bf16 v[100:103], v[132:135], v[100:103], v[44:47]
	s_waitcnt lgkmcnt(1)
	v_mfma_f32_16x16x32_bf16 v[92:95], v[92:95], v[104:107], v[48:51]
	v_mfma_f32_16x16x32_bf16 v[96:99], v[96:99], v[104:107], v[52:55]
	v_mfma_f32_16x16x32_bf16 v[128:131], v[128:131], v[104:107], v[56:59]
	v_mfma_f32_16x16x32_bf16 v[104:107], v[132:135], v[104:107], v[60:63]
	ds_read_b128 v[132:135], v111 offset:49664
	ds_read_b128 v[32:35], v109 offset:32768
	ds_read_b128 v[36:39], v109 offset:34816
	ds_read_b128 v[158:161], v111 offset:53760
	s_waitcnt lgkmcnt(2)
	v_mfma_f32_16x16x32_bf16 v[52:55], v[154:157], v[32:35], v[0:3]
	s_nop 2
	ds_read_b128 v[0:3], v111 offset:53248
	v_mfma_f32_16x16x32_bf16 v[56:59], v[132:135], v[32:35], v[4:7]
	s_nop 2
	ds_read_b128 v[4:7], v109 offset:36864
	ds_read_b128 v[168:171], v109 offset:38912
	s_waitcnt vmcnt(0)
	s_waitcnt lgkmcnt(0)
	v_mfma_f32_16x16x32_bf16 v[60:63], v[0:3], v[32:35], v[8:11]
	s_barrier
	v_mfma_f32_16x16x32_bf16 v[48:51], v[158:161], v[32:35], v[12:15]
	v_mfma_f32_16x16x32_bf16 v[44:47], v[154:157], v[36:39], v[16:19]
	v_mfma_f32_16x16x32_bf16 v[40:43], v[132:135], v[36:39], v[20:23]
	v_mfma_f32_16x16x32_bf16 v[32:35], v[0:3], v[36:39], v[24:27]
	v_mfma_f32_16x16x32_bf16 v[24:27], v[158:161], v[36:39], v[28:31]
	v_mfma_f32_16x16x32_bf16 v[36:39], v[154:157], v[4:7], v[136:139]
	v_mfma_f32_16x16x32_bf16 v[28:31], v[132:135], v[4:7], v[140:143]
	v_mfma_f32_16x16x32_bf16 v[20:23], v[0:3], v[4:7], v[150:153]
	v_mfma_f32_16x16x32_bf16 v[16:19], v[158:161], v[4:7], v[100:103]
	v_mfma_f32_16x16x32_bf16 v[12:15], v[154:157], v[168:171], v[92:95]
	v_mfma_f32_16x16x32_bf16 v[8:11], v[132:135], v[168:171], v[96:99]
	v_mfma_f32_16x16x32_bf16 v[4:7], v[0:3], v[168:171], v[128:131]
	v_mfma_f32_16x16x32_bf16 v[0:3], v[158:161], v[168:171], v[104:107]
	s_cbranch_scc0 .LBB0_1048
	s_and_b32 s10, s16, 7
	s_lshl_b32 s10, s10, 3
	s_bfe_u32 s11, s16, 0x30003
	s_or_b32 s10, s10, s11
	s_and_b32 s11, s16, 0xffffffc0
	s_or_b32 s11, s10, s11
	s_ashr_i32 s1, s11, 31
	s_lshr_b32 s1, s1, 29
	s_add_i32 s1, s11, s1
	s_lshl_b32 s3, s1, 4
	s_and_b32 s6, s3, 0xffffff80
	s_and_b32 s1, s1, 0x1fffff8
	s_sub_i32 s1, s11, s1
	s_ashr_i32 s7, s6, 31
	s_lshl_b32 s8, s1, 7
	s_lshl_b64 s[6:7], s[6:7], 13
	v_readlane_b32 s10, v245, 55
	v_readlane_b32 s11, v245, 56
	s_add_u32 s6, s10, s6
	s_addc_u32 s7, s11, s7
	s_ashr_i32 s9, s8, 31
	s_lshl_b64 s[8:9], s[8:9], 13
	s_add_u32 s8, s12, s8
	v_readfirstlane_b32 s1, v149
	s_addc_u32 s9, s13, s9
	s_mov_b32 m0, s1
	v_readfirstlane_b32 s1, v114
	global_load_lds_dwordx4 v123, s[6:7]
	v_lshl_add_u64 v[92:93], v[64:65], 1, s[8:9]
	s_mov_b32 m0, s1
	v_readfirstlane_b32 s1, v116
	global_load_lds_dwordx4 v[92:93], off
	s_mov_b32 m0, s1
	v_readfirstlane_b32 s1, v118
	global_load_lds_dwordx4 v124, s[6:7]
	v_lshl_add_u64 v[92:93], v[66:67], 1, s[8:9]
	s_mov_b32 m0, s1
	v_readfirstlane_b32 s1, v119
	global_load_lds_dwordx4 v[92:93], off
	s_mov_b32 m0, s1
	v_readfirstlane_b32 s1, v120
	global_load_lds_dwordx4 v125, s[6:7]
	v_lshl_add_u64 v[92:93], v[68:69], 1, s[8:9]
	s_mov_b32 m0, s1
	v_readfirstlane_b32 s1, v121
	global_load_lds_dwordx4 v[92:93], off
	s_mov_b32 m0, s1
	v_readfirstlane_b32 s1, v122
	global_load_lds_dwordx4 v126, s[6:7]
	v_lshl_add_u64 v[92:93], v[70:71], 1, s[8:9]
	s_mov_b32 m0, s1
	s_nop 0
	global_load_lds_dwordx4 v[92:93], off
	s_branch .LBB0_1048
